# adds: G1 epilogue arithmetic - rsqrt denormal-range guard removed (argument is mean-square + 1e-6, never denormal; v_rsq result unchanged), rope partner select uses the half-wave mask in s[4:5] instea
# speedup vs baseline: 1.0015x; 1.0015x over previous
; DI float xsum16(float x) { const u32x2 r = __builtin_amdgcn_permlane16_swap(__float_as_uint(x), __float_as_uint(x), false, false); return __uint_as_float(r[0]) + __uint_as_float(r[1]); }
; DI float xsum32(float x) { const u32x2 r = __builtin_amdgcn_permlane32_swap(__float_as_uint(x), __float_as_uint(x), false, false); return __uint_as_float(r[0]) + __uint_as_float(r[1]); }
; DI float xother32(float x) { const u32x2 r = __builtin_amdgcn_permlane32_swap(__float_as_uint(x), __float_as_uint(x), false, false); return __uint_as_float(r[0] == __float_as_uint(x) ? r[1] : r[0]); }
; template <int CT>
; DI void phase_g1(int c, int l) {
;     ...
;     for (int n = 0; n < 4; ++n) {
;       const int tt = wc * 64 + n * 16 + fr;
;       const float rs = rsqrtf(*(const float*)(shm + EXT_SSQ + tt * 4) * (1.f / 1024.f) + EPS) * (1.f / WQ_SCALE);
;       const f32x4 cs = *(const f32x4*)(shm + EXT_ROPE + tt * 64 + (fq & 1) * 16);
;       const f32x4 sn = *(const f32x4*)(shm + EXT_ROPE + tt * 64 + 32 + (fq & 1) * 16);
; #pragma unroll
;       for (int hs = 0; hs < 2; ++hs) {
;         const int f0 = fbase + wr * 128 + hs * 64;
;         const float* gain = gain_ptr(p, l, f0);
;         float v[4][4];
; #pragma unroll
;         for (int mm = 0; mm < 4; ++mm)
; #pragma unroll
;           for (int j = 0; j < 4; ++j) v[mm][j] = acc[hs * 4 + mm][n][j] * rs;
;         if (gain) {
;           float ss = 0.f;
; #pragma unroll
;           for (int mm = 0; mm < 4; ++mm)
; #pragma unroll
;             for (int j = 0; j < 4; ++j) ss += v[mm][j] * v[mm][j];
;           ss = xsum16(ss); ss = xsum32(ss);
;           const float inv = rsqrtf(ss * (1.f / 64.f) + EPS);
; #pragma unroll
;           for (int mm = 0; mm < 4; ++mm) {
;             const f32x4 gv = *(const f32x4*)(shm + EXT_GAIN + (wr * 128 + hs * 64 + mm * 16 + fq * 4) * 4);
; #pragma unroll
;             for (int j = 0; j < 4; ++j) v[mm][j] *= inv * gv[j];
;           }
; #pragma unroll
;           for (int j = 0; j < 4; ++j) {
;             const float pr = xother32(v[0][j]);
;             v[0][j] = (fq < 2) ? (v[0][j] * cs[j] - pr * sn[j]) : (v[0][j] * cs[j] + pr * sn[j]);
;           }
;         }
.LBB0_500:
	s_ashr_i32 s29, s23, 6
	v_and_b32_e32 v169, 63, v14
	s_ashr_i32 s23, s23, 8
	s_and_b32 s28, s29, 3
	v_and_b32_e32 v168, 15, v14
	s_andn2_b64 vcc, exec, s[6:7]
	v_bfe_u32 v170, v14, 4, 2
	s_cbranch_vccnz .LBB0_569
	s_cmp_gt_i32 s84, 24
	s_mov_b64 s[4:5], -1
	s_cbranch_scc1 .LBB0_566
	s_lshl_b32 s4, s23, 7
	s_add_i32 s6, s4, s24
	v_lshl_or_b32 v158, v170, 2, s4
	s_and_b32 s8, s6, 0x7ffffe00
	s_and_b32 s4, s6, 0x7fffff80
	v_lshl_or_b32 v174, s28, 6, v168
	s_cmpk_eq_i32 s4, 0x1600
	s_cselect_b32 s9, s42, 0
	s_cselect_b32 s26, s41, 0
	s_add_i32 s4, s6, 0xfffffa00
	v_lshl_or_b32 v0, v174, 2, v253
	s_lshr_b32 s4, s4, 9
	ds_read_b32 v0, v0
	s_add_i32 s4, s4, s34
	s_lshl_b32 s4, s4, 8
	s_add_u32 s27, s14, s4
	s_addc_u32 s54, s15, 0
	s_ashr_i32 s4, s6, 9
	s_add_i32 s4, s4, s34
	s_waitcnt lgkmcnt(0)
	v_fmamk_f32 v0, v0, 0x3a800000, v211
	s_lshl_b32 s4, s4, 6
	s_ashr_i32 s5, s4, 31
	s_lshl_b64 s[4:5], s[4:5], 2
	v_rsq_f32_e32 v0, v0
	s_add_u32 s7, s12, s4
	v_and_b32_e32 v173, 16, v14
	s_addc_u32 s25, s13, s5
	v_lshl_or_b32 v6, v174, 6, v173
	s_cmpk_eq_i32 s8, 0x1400
	v_add_u32_e32 v10, 0x21000, v6
	s_cselect_b32 s8, s43, s26
	s_cselect_b32 s9, s44, s9
	s_cmpk_lt_u32 s6, 0xc00
	ds_read_b128 v[6:9], v10
	ds_read_b128 v[10:13], v10 offset:32
	s_cselect_b32 s26, s54, s9
	s_cselect_b32 s27, s27, s8
	s_cmpk_lt_i32 s6, 0x600
	s_cselect_b32 s9, s25, s26
	s_cselect_b32 s8, s7, s27
	s_cmp_lg_u64 s[8:9], 0
	v_mul_f32_e32 v16, 0x3d000000, v0
	s_cselect_b64 s[8:9], -1, 0
	v_lshlrev_b32_e32 v0, 2, v158
	v_cmp_gt_u32_e64 s[4:5], 32, v169
	v_pk_mul_f32 v[154:155], v[138:139], v[16:17] op_sel_hi:[1,0]
	v_pk_mul_f32 v[156:157], v[140:141], v[16:17] op_sel_hi:[1,0]
	v_pk_mul_f32 v[146:147], v[134:135], v[16:17] op_sel_hi:[1,0]
	v_pk_mul_f32 v[152:153], v[136:137], v[16:17] op_sel_hi:[1,0]
	v_pk_mul_f32 v[144:145], v[130:131], v[16:17] op_sel_hi:[1,0]
	v_pk_mul_f32 v[150:151], v[132:133], v[16:17] op_sel_hi:[1,0]
	v_pk_mul_f32 v[142:143], v[126:127], v[16:17] op_sel_hi:[1,0]
	v_pk_mul_f32 v[148:149], v[128:129], v[16:17] op_sel_hi:[1,0]
	s_and_b64 vcc, exec, s[8:9]
	v_add_u32_e32 v171, 0x25400, v0
	v_add_u32_e32 v172, 0x25440, v0
	v_add_u32_e32 v15, 0x25480, v0
	v_add_u32_e32 v0, 0x254c0, v0
	s_cbranch_vccz .LBB0_504
	v_mul_f32_e32 v160, v155, v155
	v_pk_fma_f32 v[160:161], v[154:155], v[154:155], v[160:161] op_sel_hi:[1,1,0]
	v_mul_f32_e32 v162, v157, v157
	v_pk_fma_f32 v[160:161], v[156:157], v[156:157], v[160:161]
	s_nop 0
	v_pk_add_f32 v[160:161], v[162:163], v[160:161] op_sel_hi:[0,1]
	v_pk_fma_f32 v[160:161], v[146:147], v[146:147], v[160:161]
	v_mul_f32_e32 v162, v147, v147
	v_pk_add_f32 v[160:161], v[162:163], v[160:161] op_sel_hi:[0,1]
	v_pk_fma_f32 v[160:161], v[152:153], v[152:153], v[160:161]
	v_mul_f32_e32 v162, v153, v153
	v_pk_add_f32 v[160:161], v[162:163], v[160:161] op_sel_hi:[0,1]
	v_pk_fma_f32 v[160:161], v[144:145], v[144:145], v[160:161]
	v_mul_f32_e32 v162, v145, v145
	v_pk_add_f32 v[160:161], v[162:163], v[160:161] op_sel_hi:[0,1]
	v_pk_fma_f32 v[160:161], v[150:151], v[150:151], v[160:161]
	v_mul_f32_e32 v162, v151, v151
	v_pk_add_f32 v[160:161], v[162:163], v[160:161] op_sel_hi:[0,1]
	v_pk_fma_f32 v[160:161], v[142:143], v[142:143], v[160:161]
	v_mul_f32_e32 v162, v143, v143
	v_pk_add_f32 v[160:161], v[162:163], v[160:161] op_sel_hi:[0,1]
	v_pk_fma_f32 v[160:161], v[148:149], v[148:149], v[160:161]
	v_mul_f32_e32 v162, v149, v149
	v_pk_add_f32 v[160:161], v[162:163], v[160:161] op_sel_hi:[0,1]
	v_mov_b32_e32 v17, v160
	s_nop 1
	v_permlane16_swap_b32_e32 v160, v17
	v_add_f32_e32 v17, v160, v17
	v_mov_b32_e32 v159, v17
	s_nop 1
	v_permlane32_swap_b32_e32 v17, v159
	v_add_f32_e32 v17, v17, v159
	v_fmamk_f32 v17, v17, 0x3c800000, v211
	ds_read_b128 v[160:163], v172
	ds_read_b128 v[164:167], v171
	v_rsq_f32_e32 v17, v17
	ds_read_b128 v[176:179], v15
	v_mov_b32_e32 v180, v17
	s_waitcnt lgkmcnt(2)
	v_pk_mul_f32 v[160:161], v[160:161], v[180:181] op_sel_hi:[1,0]
	s_waitcnt lgkmcnt(0)
	v_pk_mul_f32 v[176:177], v[176:177], v[180:181] op_sel_hi:[1,0]
	v_pk_mul_f32 v[146:147], v[146:147], v[160:161]
	v_pk_mul_f32 v[160:161], v[162:163], v[180:181] op_sel_hi:[1,0]
	v_pk_mul_f32 v[144:145], v[144:145], v[176:177]
	v_pk_mul_f32 v[152:153], v[152:153], v[160:161]
	ds_read_b128 v[160:163], v0
	v_pk_mul_f32 v[176:177], v[178:179], v[180:181] op_sel_hi:[1,0]
	s_waitcnt lgkmcnt(0)
	v_pk_mul_f32 v[160:161], v[160:161], v[180:181] op_sel_hi:[1,0]
	s_nop 0
	v_pk_mul_f32 v[142:143], v[142:143], v[160:161]
	v_pk_mul_f32 v[160:161], v[162:163], v[180:181] op_sel_hi:[1,0]
	v_pk_mul_f32 v[150:151], v[150:151], v[176:177]
	v_pk_mul_f32 v[148:149], v[148:149], v[160:161]
	v_pk_mul_f32 v[160:161], v[164:165], v[180:181] op_sel_hi:[1,0]
	s_nop 0
	v_pk_mul_f32 v[154:155], v[154:155], v[160:161]
	s_nop 0
	v_mov_b32_e32 v160, v155
	v_mov_b32_e32 v161, v155
	v_mov_b32_e32 v17, v154
	v_mov_b32_e32 v159, v154
	v_permlane32_swap_b32_e32 v160, v161
	s_nop 0
	v_permlane32_swap_b32_e32 v17, v159
	v_cndmask_b32_e64 v161, v160, v161, s[4:5]
	v_cndmask_b32_e64 v160, v17, v159, s[4:5]
	v_pk_mul_f32 v[160:161], v[10:11], v[160:161]
	s_nop 0
	v_cndmask_b32_e64 v161, v161, -v161, s[4:5]
	v_cndmask_b32_e64 v160, v160, -v160, s[4:5]
	v_pk_fma_f32 v[154:155], v[6:7], v[154:155], v[160:161]
	v_pk_mul_f32 v[160:161], v[166:167], v[180:181] op_sel_hi:[1,0]
	s_nop 0
	v_pk_mul_f32 v[156:157], v[156:157], v[160:161]
	s_nop 0
	v_mov_b32_e32 v160, v157
	v_mov_b32_e32 v161, v157
	v_mov_b32_e32 v17, v156
	v_mov_b32_e32 v159, v156
	v_permlane32_swap_b32_e32 v160, v161
	s_nop 0
	v_permlane32_swap_b32_e32 v17, v159
	v_cndmask_b32_e64 v161, v160, v161, s[4:5]
	v_cndmask_b32_e64 v160, v17, v159, s[4:5]
	v_pk_mul_f32 v[160:161], v[12:13], v[160:161]
	s_nop 0
	v_cndmask_b32_e64 v161, v161, -v161, s[4:5]
	v_cndmask_b32_e64 v160, v160, -v160, s[4:5]
	v_pk_fma_f32 v[156:157], v[8:9], v[156:157], v[160:161]
; DI float xsum16(float x) { const u32x2 r = __builtin_amdgcn_permlane16_swap(__float_as_uint(x), __float_as_uint(x), false, false); return __uint_as_float(r[0]) + __uint_as_float(r[1]); }
; DI float xsum32(float x) { const u32x2 r = __builtin_amdgcn_permlane32_swap(__float_as_uint(x), __float_as_uint(x), false, false); return __uint_as_float(r[0]) + __uint_as_float(r[1]); }
; DI float xother32(float x) { const u32x2 r = __builtin_amdgcn_permlane32_swap(__float_as_uint(x), __float_as_uint(x), false, false); return __uint_as_float(r[0] == __float_as_uint(x) ? r[1] : r[0]); }
; template <int CT>
; DI void phase_g1(int c, int l) {
;     ...
;       for (int hs = 0; hs < 2; ++hs) {
;         const int f0 = fbase + wr * 128 + hs * 64;
;         const float* gain = gain_ptr(p, l, f0);
;         float v[4][4];
; #pragma unroll
;         for (int mm = 0; mm < 4; ++mm)
; #pragma unroll
;           for (int j = 0; j < 4; ++j) v[mm][j] = acc[hs * 4 + mm][n][j] * rs;
;         if (gain) {
;           float ss = 0.f;
; #pragma unroll
;           for (int mm = 0; mm < 4; ++mm)
; #pragma unroll
;             for (int j = 0; j < 4; ++j) ss += v[mm][j] * v[mm][j];
;           ss = xsum16(ss); ss = xsum32(ss);
;           const float inv = rsqrtf(ss * (1.f / 64.f) + EPS);
; #pragma unroll
;           for (int mm = 0; mm < 4; ++mm) {
;             const f32x4 gv = *(const f32x4*)(shm + EXT_GAIN + (wr * 128 + hs * 64 + mm * 16 + fq * 4) * 4);
; #pragma unroll
;             for (int j = 0; j < 4; ++j) v[mm][j] *= inv * gv[j];
;           }
; #pragma unroll
;           for (int j = 0; j < 4; ++j) {
;             const float pr = xother32(v[0][j]);
;             v[0][j] = (fq < 2) ? (v[0][j] * cs[j] - pr * sn[j]) : (v[0][j] * cs[j] + pr * sn[j]);
;           }
;         }
; #pragma unroll
;         for (int mm = 0; mm < 4; ++mm) {
;           uint2 o; o.x = pk2(v[mm][0], v[mm][1]); o.y = pk2(v[mm][2], v[mm][3]);
;           *(uint2*)(shm + tt * TP + (wr * 128 + hs * 64 + mm * 16 + fq * 4) * 2) = o;
;         }
.LBB0_504:
	s_or_b32 s6, s6, 64
	s_cmpk_lt_i32 s6, 0x600
	s_cselect_b32 s73, s25, s26
	s_cselect_b32 s72, s7, s27
	v_lshlrev_b32_e32 v175, 1, v158
	s_cmp_lg_u64 s[72:73], 0
	v_mov_b32_e32 v17, v16
	v_cvt_pk_bf16_f32 v154, v154, v155
	v_cvt_pk_bf16_f32 v155, v156, v157
	v_mad_u32_u24 v156, v174, s82, v175
	v_cvt_pk_bf16_f32 v146, v146, v147
	v_cvt_pk_bf16_f32 v147, v152, v153
	v_cvt_pk_bf16_f32 v144, v144, v145
	v_cvt_pk_bf16_f32 v145, v150, v151
	v_cvt_pk_bf16_f32 v142, v142, v143
	v_cvt_pk_bf16_f32 v143, v148, v149
	s_cselect_b64 s[26:27], -1, 0
	ds_write2_b64 v156, v[154:155], v[146:147] offset1:4
	ds_write2_b64 v156, v[144:145], v[142:143] offset0:8 offset1:12
	v_pk_mul_f32 v[144:145], v[122:123], v[16:17]
	v_pk_mul_f32 v[148:149], v[124:125], v[16:17]
	v_pk_mul_f32 v[142:143], v[118:119], v[16:17]
	v_pk_mul_f32 v[146:147], v[120:121], v[16:17]
	v_pk_mul_f32 v[150:151], v[114:115], v[16:17]
	v_pk_mul_f32 v[152:153], v[116:117], v[16:17]
	v_pk_mul_f32 v[154:155], v[106:107], v[16:17]
	v_pk_mul_f32 v[16:17], v[108:109], v[16:17]
	s_and_b64 vcc, exec, s[26:27]
	v_or_b32_e32 v176, 64, v158
	s_cbranch_vccz .LBB0_571
	v_mul_f32_e32 v156, v145, v145
	v_pk_fma_f32 v[156:157], v[144:145], v[144:145], v[156:157] op_sel_hi:[1,1,0]
	v_mul_f32_e32 v160, v149, v149
	v_pk_fma_f32 v[156:157], v[148:149], v[148:149], v[156:157]
	v_or_b32_e32 v177, 64, v158
	v_pk_add_f32 v[156:157], v[160:161], v[156:157] op_sel_hi:[0,1]
	v_pk_fma_f32 v[156:157], v[142:143], v[142:143], v[156:157]
	v_mul_f32_e32 v160, v143, v143
	v_pk_add_f32 v[156:157], v[160:161], v[156:157] op_sel_hi:[0,1]
	v_pk_fma_f32 v[156:157], v[146:147], v[146:147], v[156:157]
	v_mul_f32_e32 v160, v147, v147
	v_pk_add_f32 v[156:157], v[160:161], v[156:157] op_sel_hi:[0,1]
	v_pk_fma_f32 v[156:157], v[150:151], v[150:151], v[156:157]
	v_mul_f32_e32 v160, v151, v151
	v_pk_add_f32 v[156:157], v[160:161], v[156:157] op_sel_hi:[0,1]
	v_pk_fma_f32 v[156:157], v[152:153], v[152:153], v[156:157]
	v_mul_f32_e32 v160, v153, v153
	v_pk_add_f32 v[156:157], v[160:161], v[156:157] op_sel_hi:[0,1]
	v_pk_fma_f32 v[156:157], v[154:155], v[154:155], v[156:157]
	v_mul_f32_e32 v160, v155, v155
	v_pk_add_f32 v[156:157], v[160:161], v[156:157] op_sel_hi:[0,1]
	v_pk_fma_f32 v[156:157], v[16:17], v[16:17], v[156:157]
	v_mul_f32_e32 v160, v17, v17
	v_pk_add_f32 v[156:157], v[160:161], v[156:157] op_sel_hi:[0,1]
	v_mov_b32_e32 v157, v156
	s_nop 1
	v_permlane16_swap_b32_e32 v156, v157
	v_add_f32_e32 v156, v156, v157
	v_mov_b32_e32 v157, v156
	s_nop 1
	v_permlane32_swap_b32_e32 v156, v157
	v_add_f32_e32 v156, v156, v157
	v_fmamk_f32 v156, v156, 0x3c800000, v211
	v_lshlrev_b32_e32 v161, 2, v177
	v_add_u32_e32 v162, 0x25400, v161
	v_rsq_f32_e32 v160, v156
	ds_read_b128 v[178:181], v162
	v_add_u32_e32 v156, 0x25440, v161
	ds_read_b128 v[156:159], v156
	v_mov_b32_e32 v186, v160
	v_add_u32_e32 v160, 0x25480, v161
	ds_read_b128 v[162:165], v160
	v_add_u32_e32 v160, 0x254c0, v161
	ds_read_b128 v[182:185], v160
	s_waitcnt lgkmcnt(3)
	v_pk_mul_f32 v[178:179], v[178:179], v[186:187] op_sel_hi:[1,0]
	s_waitcnt lgkmcnt(2)
	v_pk_mul_f32 v[156:157], v[156:157], v[186:187] op_sel_hi:[1,0]
	s_waitcnt lgkmcnt(1)
	v_pk_mul_f32 v[160:161], v[162:163], v[186:187] op_sel_hi:[1,0]
	v_pk_mul_f32 v[178:179], v[144:145], v[178:179]
	v_pk_mul_f32 v[162:163], v[150:151], v[160:161]
	v_pk_mul_f32 v[160:161], v[164:165], v[186:187] op_sel_hi:[1,0]
	s_waitcnt lgkmcnt(0)
	v_pk_mul_f32 v[166:167], v[184:185], v[186:187] op_sel_hi:[1,0]
	v_pk_mul_f32 v[164:165], v[152:153], v[160:161]
	v_pk_mul_f32 v[160:161], v[182:183], v[186:187] op_sel_hi:[1,0]
	v_mov_b32_e32 v183, v179
	v_mov_b32_e32 v185, v179
	v_mov_b32_e32 v182, v178
	v_mov_b32_e32 v184, v178
	v_permlane32_swap_b32_e32 v183, v185
	s_nop 0
	v_permlane32_swap_b32_e32 v182, v184
	v_pk_mul_f32 v[158:159], v[158:159], v[186:187] op_sel_hi:[1,0]
	v_pk_mul_f32 v[156:157], v[142:143], v[156:157]
	v_cndmask_b32_e64 v183, v183, v185, s[4:5]
	v_pk_mul_f32 v[158:159], v[146:147], v[158:159]
	v_pk_mul_f32 v[160:161], v[154:155], v[160:161]
	v_cndmask_b32_e64 v182, v182, v184, s[4:5]
	v_pk_mul_f32 v[10:11], v[10:11], v[182:183]
	v_pk_mul_f32 v[166:167], v[16:17], v[166:167]
	v_cndmask_b32_e64 v11, v11, -v11, s[4:5]
	v_cndmask_b32_e64 v10, v10, -v10, s[4:5]
	v_pk_fma_f32 v[6:7], v[6:7], v[178:179], v[10:11]
	v_pk_mul_f32 v[10:11], v[180:181], v[186:187] op_sel_hi:[1,0]
	s_nop 0
	v_pk_mul_f32 v[10:11], v[148:149], v[10:11]
	s_nop 0
	v_mov_b32_e32 v179, v11
	v_mov_b32_e32 v181, v11
	v_mov_b32_e32 v178, v10
	v_mov_b32_e32 v180, v10
	v_permlane32_swap_b32_e32 v179, v181
	s_nop 0
	v_permlane32_swap_b32_e32 v178, v180
	v_cndmask_b32_e64 v179, v179, v181, s[4:5]
	v_cndmask_b32_e64 v178, v178, v180, s[4:5]
	v_pk_mul_f32 v[12:13], v[12:13], v[178:179]
	s_nop 0
	v_cndmask_b32_e64 v13, v13, -v13, s[4:5]
	v_cndmask_b32_e64 v12, v12, -v12, s[4:5]
	v_pk_fma_f32 v[8:9], v[8:9], v[10:11], v[12:13]
	s_cbranch_execnz .LBB0_507

; DI float xsum16(float x) { const u32x2 r = __builtin_amdgcn_permlane16_swap(__float_as_uint(x), __float_as_uint(x), false, false); return __uint_as_float(r[0]) + __uint_as_float(r[1]); }
; DI float xsum32(float x) { const u32x2 r = __builtin_amdgcn_permlane32_swap(__float_as_uint(x), __float_as_uint(x), false, false); return __uint_as_float(r[0]) + __uint_as_float(r[1]); }
; DI float xother32(float x) { const u32x2 r = __builtin_amdgcn_permlane32_swap(__float_as_uint(x), __float_as_uint(x), false, false); return __uint_as_float(r[0] == __float_as_uint(x) ? r[1] : r[0]); }
; template <int CT>
; DI void phase_g1(int c, int l) {
;     ...
;     for (int n = 0; n < 4; ++n) {
;       const int tt = wc * 64 + n * 16 + fr;
;       const float rs = rsqrtf(*(const float*)(shm + EXT_SSQ + tt * 4) * (1.f / 1024.f) + EPS) * (1.f / WQ_SCALE);
;       const f32x4 cs = *(const f32x4*)(shm + EXT_ROPE + tt * 64 + (fq & 1) * 16);
;       const f32x4 sn = *(const f32x4*)(shm + EXT_ROPE + tt * 64 + 32 + (fq & 1) * 16);
; #pragma unroll
;       for (int hs = 0; hs < 2; ++hs) {
;         const int f0 = fbase + wr * 128 + hs * 64;
;         const float* gain = gain_ptr(p, l, f0);
;         float v[4][4];
; #pragma unroll
;         for (int mm = 0; mm < 4; ++mm)
; #pragma unroll
;           for (int j = 0; j < 4; ++j) v[mm][j] = acc[hs * 4 + mm][n][j] * rs;
;         if (gain) {
;           float ss = 0.f;
; #pragma unroll
;           for (int mm = 0; mm < 4; ++mm)
; #pragma unroll
;             for (int j = 0; j < 4; ++j) ss += v[mm][j] * v[mm][j];
;           ss = xsum16(ss); ss = xsum32(ss);
;           const float inv = rsqrtf(ss * (1.f / 64.f) + EPS);
; #pragma unroll
;           for (int mm = 0; mm < 4; ++mm) {
;             const f32x4 gv = *(const f32x4*)(shm + EXT_GAIN + (wr * 128 + hs * 64 + mm * 16 + fq * 4) * 4);
; #pragma unroll
;             for (int j = 0; j < 4; ++j) v[mm][j] *= inv * gv[j];
;           }
; #pragma unroll
;           for (int j = 0; j < 4; ++j) {
;             const float pr = xother32(v[0][j]);
;             v[0][j] = (fq < 2) ? (v[0][j] * cs[j] - pr * sn[j]) : (v[0][j] * cs[j] + pr * sn[j]);
;           }
;         }
.LBB0_507:
	v_mul_u32_u24_e32 v178, 0x210, v174
	v_lshlrev_b32_e32 v176, 1, v177
	s_waitcnt lgkmcnt(3)
	v_cvt_pk_bf16_f32 v6, v6, v7
	v_cvt_pk_bf16_f32 v7, v8, v9
	s_waitcnt lgkmcnt(2)
	v_add_u32_e32 v10, v178, v176
	v_cvt_pk_bf16_f32 v8, v156, v157
	v_cvt_pk_bf16_f32 v9, v158, v159
	ds_write2_b64 v10, v[6:7], v[8:9] offset1:4
	v_cvt_pk_bf16_f32 v6, v162, v163
	v_cvt_pk_bf16_f32 v7, v164, v165
	v_cvt_pk_bf16_f32 v8, v160, v161
	v_cvt_pk_bf16_f32 v9, v166, v167
	ds_write2_b64 v10, v[6:7], v[8:9] offset0:8 offset1:12
	v_or_b32_e32 v6, 16, v174
	v_lshl_or_b32 v7, v6, 2, v253
	ds_read_b32 v10, v7
	v_lshl_or_b32 v6, v6, 6, v173
	v_add_u32_e32 v11, 0x21000, v6
	ds_read_b128 v[6:9], v11
	s_waitcnt lgkmcnt(1)
	v_fmamk_f32 v10, v10, 0x3a800000, v211
	v_rsq_f32_e32 v10, v10
	s_nop 0
	v_mul_f32_e32 v16, 0x3d000000, v10
	ds_read_b128 v[10:13], v11 offset:32
	v_pk_mul_f32 v[154:155], v[102:103], v[16:17] op_sel_hi:[1,0]
	v_pk_mul_f32 v[156:157], v[104:105], v[16:17] op_sel_hi:[1,0]
	v_pk_mul_f32 v[146:147], v[98:99], v[16:17] op_sel_hi:[1,0]
	v_pk_mul_f32 v[150:151], v[100:101], v[16:17] op_sel_hi:[1,0]
	v_pk_mul_f32 v[144:145], v[94:95], v[16:17] op_sel_hi:[1,0]
	v_pk_mul_f32 v[148:149], v[96:97], v[16:17] op_sel_hi:[1,0]
	v_pk_mul_f32 v[142:143], v[90:91], v[16:17] op_sel_hi:[1,0]
	v_cndmask_b32_e64 v17, 0, 1, s[8:9]
	v_cmp_ne_u32_e64 s[6:7], 1, v17
	s_andn2_b64 vcc, exec, s[8:9]
	v_pk_mul_f32 v[152:153], v[92:93], v[16:17] op_sel_hi:[1,0]
	s_cbranch_vccnz .LBB0_509
	v_mul_f32_e32 v158, v155, v155
	v_pk_fma_f32 v[158:159], v[154:155], v[154:155], v[158:159] op_sel_hi:[1,1,0]
	v_mul_f32_e32 v160, v157, v157
	v_pk_fma_f32 v[158:159], v[156:157], v[156:157], v[158:159]
	s_nop 0
	v_pk_add_f32 v[158:159], v[160:161], v[158:159] op_sel_hi:[0,1]
	v_pk_fma_f32 v[158:159], v[146:147], v[146:147], v[158:159]
	v_mul_f32_e32 v160, v147, v147
	v_pk_add_f32 v[158:159], v[160:161], v[158:159] op_sel_hi:[0,1]
	v_pk_fma_f32 v[158:159], v[150:151], v[150:151], v[158:159]
	v_mul_f32_e32 v160, v151, v151
	v_pk_add_f32 v[158:159], v[160:161], v[158:159] op_sel_hi:[0,1]
	v_pk_fma_f32 v[158:159], v[144:145], v[144:145], v[158:159]
	v_mul_f32_e32 v160, v145, v145
	v_pk_add_f32 v[158:159], v[160:161], v[158:159] op_sel_hi:[0,1]
	v_pk_fma_f32 v[158:159], v[148:149], v[148:149], v[158:159]
	v_mul_f32_e32 v160, v149, v149
	v_pk_add_f32 v[158:159], v[160:161], v[158:159] op_sel_hi:[0,1]
	v_pk_fma_f32 v[158:159], v[142:143], v[142:143], v[158:159]
	v_mul_f32_e32 v160, v143, v143
	v_pk_add_f32 v[158:159], v[160:161], v[158:159] op_sel_hi:[0,1]
	v_pk_fma_f32 v[158:159], v[152:153], v[152:153], v[158:159]
	v_mul_f32_e32 v160, v153, v153
	v_pk_add_f32 v[158:159], v[160:161], v[158:159] op_sel_hi:[0,1]
	v_mov_b32_e32 v17, v158
	s_nop 1
	v_permlane16_swap_b32_e32 v158, v17
	v_add_f32_e32 v17, v158, v17
	v_mov_b32_e32 v158, v17
	s_nop 1
	v_permlane32_swap_b32_e32 v17, v158
	v_add_f32_e32 v17, v17, v158
	v_fmamk_f32 v17, v17, 0x3c800000, v211
	v_rsq_f32_e32 v17, v17
	ds_read_b128 v[158:161], v172
	ds_read_b128 v[162:165], v171
	ds_read_b128 v[180:183], v15
	v_mov_b32_e32 v166, v17
	s_waitcnt lgkmcnt(2)
	v_pk_mul_f32 v[158:159], v[158:159], v[166:167] op_sel_hi:[1,0]
	s_waitcnt lgkmcnt(0)
	v_pk_mul_f32 v[180:181], v[180:181], v[166:167] op_sel_hi:[1,0]
	v_pk_mul_f32 v[146:147], v[146:147], v[158:159]
	v_pk_mul_f32 v[158:159], v[160:161], v[166:167] op_sel_hi:[1,0]
	v_pk_mul_f32 v[144:145], v[144:145], v[180:181]
	v_pk_mul_f32 v[150:151], v[150:151], v[158:159]
	ds_read_b128 v[158:161], v0
	v_pk_mul_f32 v[180:181], v[182:183], v[166:167] op_sel_hi:[1,0]
	s_waitcnt lgkmcnt(0)
	v_pk_mul_f32 v[158:159], v[158:159], v[166:167] op_sel_hi:[1,0]
	s_nop 0
	v_pk_mul_f32 v[142:143], v[142:143], v[158:159]
	v_pk_mul_f32 v[158:159], v[160:161], v[166:167] op_sel_hi:[1,0]
	v_pk_mul_f32 v[148:149], v[148:149], v[180:181]
	v_pk_mul_f32 v[152:153], v[152:153], v[158:159]
	v_pk_mul_f32 v[158:159], v[162:163], v[166:167] op_sel_hi:[1,0]
	s_nop 0
	v_pk_mul_f32 v[154:155], v[154:155], v[158:159]
	s_nop 0
	v_mov_b32_e32 v159, v155
	v_mov_b32_e32 v160, v155
	v_mov_b32_e32 v17, v154
	v_mov_b32_e32 v158, v154
	v_permlane32_swap_b32_e32 v159, v160
	s_nop 0
	v_permlane32_swap_b32_e32 v17, v158
	v_cndmask_b32_e64 v159, v159, v160, s[4:5]
	v_cndmask_b32_e64 v158, v17, v158, s[4:5]
	v_pk_mul_f32 v[158:159], v[10:11], v[158:159]
	s_nop 0
	v_cndmask_b32_e64 v159, v159, -v159, s[4:5]
	v_cndmask_b32_e64 v158, v158, -v158, s[4:5]
	v_pk_fma_f32 v[154:155], v[6:7], v[154:155], v[158:159]
	v_pk_mul_f32 v[158:159], v[164:165], v[166:167] op_sel_hi:[1,0]
	s_nop 0
	v_pk_mul_f32 v[156:157], v[156:157], v[158:159]
	s_nop 0
	v_mov_b32_e32 v159, v157
	v_mov_b32_e32 v160, v157
	v_mov_b32_e32 v17, v156
	v_mov_b32_e32 v158, v156
	v_permlane32_swap_b32_e32 v159, v160
	s_nop 0
	v_permlane32_swap_b32_e32 v17, v158
	v_cndmask_b32_e64 v159, v159, v160, s[4:5]
	v_cndmask_b32_e64 v158, v17, v158, s[4:5]
	v_pk_mul_f32 v[158:159], v[12:13], v[158:159]
	s_nop 0
	v_cndmask_b32_e64 v159, v159, -v159, s[4:5]
	v_cndmask_b32_e64 v158, v158, -v158, s[4:5]
	v_pk_fma_f32 v[156:157], v[8:9], v[156:157], v[158:159]
; DI float xsum16(float x) { const u32x2 r = __builtin_amdgcn_permlane16_swap(__float_as_uint(x), __float_as_uint(x), false, false); return __uint_as_float(r[0]) + __uint_as_float(r[1]); }
; DI float xsum32(float x) { const u32x2 r = __builtin_amdgcn_permlane32_swap(__float_as_uint(x), __float_as_uint(x), false, false); return __uint_as_float(r[0]) + __uint_as_float(r[1]); }
; template <int CT>
; DI void phase_g1(int c, int l) {
;     ...
;     for (int n = 0; n < 4; ++n) {
;       const int tt = wc * 64 + n * 16 + fr;
;       const float rs = rsqrtf(*(const float*)(shm + EXT_SSQ + tt * 4) * (1.f / 1024.f) + EPS) * (1.f / WQ_SCALE);
;       const f32x4 cs = *(const f32x4*)(shm + EXT_ROPE + tt * 64 + (fq & 1) * 16);
;       const f32x4 sn = *(const f32x4*)(shm + EXT_ROPE + tt * 64 + 32 + (fq & 1) * 16);
; #pragma unroll
;       for (int hs = 0; hs < 2; ++hs) {
;         const int f0 = fbase + wr * 128 + hs * 64;
;         const float* gain = gain_ptr(p, l, f0);
;         float v[4][4];
; #pragma unroll
;         for (int mm = 0; mm < 4; ++mm)
; #pragma unroll
;           for (int j = 0; j < 4; ++j) v[mm][j] = acc[hs * 4 + mm][n][j] * rs;
;         if (gain) {
;           float ss = 0.f;
; #pragma unroll
;           for (int mm = 0; mm < 4; ++mm)
; #pragma unroll
;             for (int j = 0; j < 4; ++j) ss += v[mm][j] * v[mm][j];
;           ss = xsum16(ss); ss = xsum32(ss);
;           const float inv = rsqrtf(ss * (1.f / 64.f) + EPS);
; #pragma unroll
;           for (int mm = 0; mm < 4; ++mm) {
;             const f32x4 gv = *(const f32x4*)(shm + EXT_GAIN + (wr * 128 + hs * 64 + mm * 16 + fq * 4) * 4);
; #pragma unroll
;             for (int j = 0; j < 4; ++j) v[mm][j] *= inv * gv[j];
;           }
; #pragma unroll
;           for (int j = 0; j < 4; ++j) {
;             const float pr = xother32(v[0][j]);
;             v[0][j] = (fq < 2) ? (v[0][j] * cs[j] - pr * sn[j]) : (v[0][j] * cs[j] + pr * sn[j]);
;           }
;         }
; #pragma unroll
;         for (int mm = 0; mm < 4; ++mm) {
;           uint2 o; o.x = pk2(v[mm][0], v[mm][1]); o.y = pk2(v[mm][2], v[mm][3]);
;           *(uint2*)(shm + tt * TP + (wr * 128 + hs * 64 + mm * 16 + fq * 4) * 2) = o;
;         }
.LBB0_509:
	v_add_u32_e32 v162, 0x2100, v178
	v_cvt_pk_bf16_f32 v154, v154, v155
	v_cvt_pk_bf16_f32 v155, v156, v157
	v_add_u32_e32 v156, v162, v175
	v_cvt_pk_bf16_f32 v146, v146, v147
	v_cvt_pk_bf16_f32 v147, v150, v151
	v_cvt_pk_bf16_f32 v144, v144, v145
	v_cvt_pk_bf16_f32 v145, v148, v149
	v_cvt_pk_bf16_f32 v142, v142, v143
	v_cvt_pk_bf16_f32 v143, v152, v153
	ds_write2_b64 v156, v[154:155], v[146:147] offset1:4
	ds_write2_b64 v156, v[144:145], v[142:143] offset0:8 offset1:12
	v_cndmask_b32_e64 v156, 0, 1, s[26:27]
	v_mov_b32_e32 v17, v16
	v_cmp_ne_u32_e64 s[8:9], 1, v156
	v_lshlrev_b32_e32 v156, 2, v177
	v_pk_mul_f32 v[152:153], v[110:111], v[16:17]
	v_pk_mul_f32 v[154:155], v[112:113], v[16:17]
	v_pk_mul_f32 v[146:147], v[86:87], v[16:17]
	v_pk_mul_f32 v[150:151], v[88:89], v[16:17]
	v_pk_mul_f32 v[144:145], v[82:83], v[16:17]
	v_pk_mul_f32 v[148:149], v[84:85], v[16:17]
	v_pk_mul_f32 v[142:143], v[78:79], v[16:17]
	v_pk_mul_f32 v[16:17], v[80:81], v[16:17]
	s_andn2_b64 vcc, exec, s[26:27]
	v_add_u32_e32 v160, 0x25400, v156
	v_add_u32_e32 v161, 0x25440, v156
	v_add_u32_e32 v158, 0x25480, v156
	v_add_u32_e32 v159, 0x254c0, v156
	s_cbranch_vccnz .LBB0_511
	v_mul_f32_e32 v156, v153, v153
	v_pk_fma_f32 v[156:157], v[152:153], v[152:153], v[156:157] op_sel_hi:[1,1,0]
	v_mul_f32_e32 v164, v155, v155
	v_pk_fma_f32 v[156:157], v[154:155], v[154:155], v[156:157]
	s_nop 0
	v_pk_add_f32 v[156:157], v[164:165], v[156:157] op_sel_hi:[0,1]
	v_pk_fma_f32 v[156:157], v[146:147], v[146:147], v[156:157]
	v_mul_f32_e32 v164, v147, v147
	v_pk_add_f32 v[156:157], v[164:165], v[156:157] op_sel_hi:[0,1]
	v_pk_fma_f32 v[156:157], v[150:151], v[150:151], v[156:157]
	v_mul_f32_e32 v164, v151, v151
	v_pk_add_f32 v[156:157], v[164:165], v[156:157] op_sel_hi:[0,1]
	v_pk_fma_f32 v[156:157], v[144:145], v[144:145], v[156:157]
	v_mul_f32_e32 v164, v145, v145
	v_pk_add_f32 v[156:157], v[164:165], v[156:157] op_sel_hi:[0,1]
	v_pk_fma_f32 v[156:157], v[148:149], v[148:149], v[156:157]
	v_mul_f32_e32 v164, v149, v149
	v_pk_add_f32 v[156:157], v[164:165], v[156:157] op_sel_hi:[0,1]
	v_pk_fma_f32 v[156:157], v[142:143], v[142:143], v[156:157]
	v_mul_f32_e32 v164, v143, v143
	v_pk_add_f32 v[156:157], v[164:165], v[156:157] op_sel_hi:[0,1]
	v_pk_fma_f32 v[156:157], v[16:17], v[16:17], v[156:157]
	v_mul_f32_e32 v164, v17, v17
	v_pk_add_f32 v[156:157], v[164:165], v[156:157] op_sel_hi:[0,1]
	v_mov_b32_e32 v157, v156
	s_nop 1
	v_permlane16_swap_b32_e32 v156, v157
	v_add_f32_e32 v156, v156, v157
	v_mov_b32_e32 v157, v156
	s_nop 1
	v_permlane32_swap_b32_e32 v156, v157
	v_add_f32_e32 v156, v156, v157
	v_fmamk_f32 v156, v156, 0x3c800000, v211
	ds_read2_b32 v[164:165], v160 offset0:2 offset1:3
	ds_read2_b32 v[166:167], v161 offset0:2 offset1:3
	ds_read2_b32 v[178:179], v161 offset1:1
	ds_read2_b32 v[180:181], v160 offset1:1
	ds_read2_b32 v[182:183], v158 offset0:2 offset1:3
	ds_read2_b32 v[184:185], v159 offset0:2 offset1:3
	ds_read2_b32 v[186:187], v159 offset1:1
	ds_read2_b32 v[188:189], v158 offset1:1
	v_rsq_f32_e32 v156, v156
	s_nop 0
	s_waitcnt lgkmcnt(6)
	v_pk_mul_f32 v[166:167], v[166:167], v[156:157] op_sel_hi:[1,0]
	s_waitcnt lgkmcnt(5)
	v_pk_mul_f32 v[178:179], v[178:179], v[156:157] op_sel_hi:[1,0]
	v_pk_mul_f32 v[150:151], v[150:151], v[166:167]
	s_waitcnt lgkmcnt(0)
	v_pk_mul_f32 v[166:167], v[188:189], v[156:157] op_sel_hi:[1,0]
	v_pk_mul_f32 v[146:147], v[146:147], v[178:179]
	v_pk_mul_f32 v[144:145], v[144:145], v[166:167]
	v_pk_mul_f32 v[166:167], v[182:183], v[156:157] op_sel_hi:[1,0]
	s_nop 0
	v_pk_mul_f32 v[148:149], v[148:149], v[166:167]
	v_pk_mul_f32 v[166:167], v[186:187], v[156:157] op_sel_hi:[1,0]
	s_nop 0
	v_pk_mul_f32 v[142:143], v[142:143], v[166:167]
	v_pk_mul_f32 v[166:167], v[184:185], v[156:157] op_sel_hi:[1,0]
	s_nop 0
	v_pk_mul_f32 v[16:17], v[16:17], v[166:167]
	v_pk_mul_f32 v[166:167], v[180:181], v[156:157] op_sel_hi:[1,0]
	s_nop 0
	v_pk_mul_f32 v[152:153], v[152:153], v[166:167]
	s_nop 0
	v_mov_b32_e32 v166, v153
	v_mov_b32_e32 v167, v153
	v_mov_b32_e32 v157, v152
	v_mov_b32_e32 v163, v152
	v_permlane32_swap_b32_e32 v166, v167
	s_nop 0
	v_permlane32_swap_b32_e32 v157, v163
	v_cndmask_b32_e64 v167, v166, v167, s[4:5]
	v_cndmask_b32_e64 v166, v157, v163, s[4:5]
	v_pk_mul_f32 v[10:11], v[10:11], v[166:167]
	s_nop 0
	v_cndmask_b32_e64 v11, v11, -v11, s[4:5]
	v_cndmask_b32_e64 v10, v10, -v10, s[4:5]
	v_pk_fma_f32 v[152:153], v[6:7], v[152:153], v[10:11]
	v_pk_mul_f32 v[6:7], v[164:165], v[156:157] op_sel_hi:[1,0]
	s_nop 0
	v_pk_mul_f32 v[6:7], v[154:155], v[6:7]
	s_nop 0
	v_mov_b32_e32 v11, v7
	v_mov_b32_e32 v155, v7
	v_mov_b32_e32 v10, v6
	v_mov_b32_e32 v154, v6
	v_permlane32_swap_b32_e32 v11, v155
	s_nop 0
	v_permlane32_swap_b32_e32 v10, v154
	v_cndmask_b32_e64 v11, v11, v155, s[4:5]
	v_cndmask_b32_e64 v10, v10, v154, s[4:5]
	v_pk_mul_f32 v[10:11], v[12:13], v[10:11]
	s_nop 0
	v_cndmask_b32_e64 v11, v11, -v11, s[4:5]
	v_cndmask_b32_e64 v10, v10, -v10, s[4:5]
	v_pk_fma_f32 v[154:155], v[8:9], v[6:7], v[10:11]
; DI float xsum16(float x) { const u32x2 r = __builtin_amdgcn_permlane16_swap(__float_as_uint(x), __float_as_uint(x), false, false); return __uint_as_float(r[0]) + __uint_as_float(r[1]); }
; DI float xsum32(float x) { const u32x2 r = __builtin_amdgcn_permlane32_swap(__float_as_uint(x), __float_as_uint(x), false, false); return __uint_as_float(r[0]) + __uint_as_float(r[1]); }
; template <int CT>
; DI void phase_g1(int c, int l) {
;     ...
;     for (int n = 0; n < 4; ++n) {
;       const int tt = wc * 64 + n * 16 + fr;
;       const float rs = rsqrtf(*(const float*)(shm + EXT_SSQ + tt * 4) * (1.f / 1024.f) + EPS) * (1.f / WQ_SCALE);
;       const f32x4 cs = *(const f32x4*)(shm + EXT_ROPE + tt * 64 + (fq & 1) * 16);
;       const f32x4 sn = *(const f32x4*)(shm + EXT_ROPE + tt * 64 + 32 + (fq & 1) * 16);
; #pragma unroll
;       for (int hs = 0; hs < 2; ++hs) {
;         const int f0 = fbase + wr * 128 + hs * 64;
;         const float* gain = gain_ptr(p, l, f0);
;         float v[4][4];
; #pragma unroll
;         for (int mm = 0; mm < 4; ++mm)
; #pragma unroll
;           for (int j = 0; j < 4; ++j) v[mm][j] = acc[hs * 4 + mm][n][j] * rs;
;         if (gain) {
;           float ss = 0.f;
; #pragma unroll
;           for (int mm = 0; mm < 4; ++mm)
; #pragma unroll
;             for (int j = 0; j < 4; ++j) ss += v[mm][j] * v[mm][j];
;           ss = xsum16(ss); ss = xsum32(ss);
;           const float inv = rsqrtf(ss * (1.f / 64.f) + EPS);
; #pragma unroll
;           for (int mm = 0; mm < 4; ++mm) {
;             const f32x4 gv = *(const f32x4*)(shm + EXT_GAIN + (wr * 128 + hs * 64 + mm * 16 + fq * 4) * 4);
; #pragma unroll
;             for (int j = 0; j < 4; ++j) v[mm][j] *= inv * gv[j];
;           }
; #pragma unroll
;           for (int j = 0; j < 4; ++j) {
;             const float pr = xother32(v[0][j]);
;             v[0][j] = (fq < 2) ? (v[0][j] * cs[j] - pr * sn[j]) : (v[0][j] * cs[j] + pr * sn[j]);
;           }
;         }
; #pragma unroll
;         for (int mm = 0; mm < 4; ++mm) {
;           uint2 o; o.x = pk2(v[mm][0], v[mm][1]); o.y = pk2(v[mm][2], v[mm][3]);
;           *(uint2*)(shm + tt * TP + (wr * 128 + hs * 64 + mm * 16 + fq * 4) * 2) = o;
;         }
.LBB0_511:
	s_waitcnt lgkmcnt(3)
	v_cvt_pk_bf16_f32 v6, v152, v153
	v_cvt_pk_bf16_f32 v7, v154, v155
	s_waitcnt lgkmcnt(2)
	v_add_u32_e32 v10, v162, v176
	v_cvt_pk_bf16_f32 v8, v146, v147
	v_cvt_pk_bf16_f32 v9, v150, v151
	ds_write2_b64 v10, v[6:7], v[8:9] offset1:4
	v_cvt_pk_bf16_f32 v6, v144, v145
	v_cvt_pk_bf16_f32 v7, v148, v149
	v_cvt_pk_bf16_f32 v8, v142, v143
	v_cvt_pk_bf16_f32 v9, v16, v17
	ds_write2_b64 v10, v[6:7], v[8:9] offset0:8 offset1:12
	v_or_b32_e32 v6, 32, v174
	v_lshl_or_b32 v7, v6, 2, v253
	ds_read_b32 v10, v7
	v_lshl_or_b32 v6, v6, 6, v173
	v_add_u32_e32 v11, 0x21000, v6
	ds_read_b128 v[6:9], v11
	s_waitcnt lgkmcnt(1)
	v_fmamk_f32 v10, v10, 0x3a800000, v211
	v_rsq_f32_e32 v10, v10
	s_nop 0
	v_mul_f32_e32 v16, 0x3d000000, v10
	ds_read_b128 v[10:13], v11 offset:32
	v_pk_mul_f32 v[154:155], v[74:75], v[16:17] op_sel_hi:[1,0]
	v_pk_mul_f32 v[156:157], v[76:77], v[16:17] op_sel_hi:[1,0]
	v_pk_mul_f32 v[146:147], v[70:71], v[16:17] op_sel_hi:[1,0]
	v_pk_mul_f32 v[150:151], v[72:73], v[16:17] op_sel_hi:[1,0]
	v_pk_mul_f32 v[144:145], v[66:67], v[16:17] op_sel_hi:[1,0]
	v_pk_mul_f32 v[148:149], v[68:69], v[16:17] op_sel_hi:[1,0]
	v_pk_mul_f32 v[142:143], v[62:63], v[16:17] op_sel_hi:[1,0]
	s_and_b64 vcc, exec, s[6:7]
	v_pk_mul_f32 v[152:153], v[64:65], v[16:17] op_sel_hi:[1,0]
	s_cbranch_vccnz .LBB0_513
	v_mul_f32_e32 v164, v155, v155
	v_pk_fma_f32 v[164:165], v[154:155], v[154:155], v[164:165] op_sel_hi:[1,1,0]
	v_mul_f32_e32 v166, v157, v157
	v_pk_fma_f32 v[164:165], v[156:157], v[156:157], v[164:165]
	s_nop 0
	v_pk_add_f32 v[164:165], v[166:167], v[164:165] op_sel_hi:[0,1]
	v_pk_fma_f32 v[164:165], v[146:147], v[146:147], v[164:165]
	v_mul_f32_e32 v166, v147, v147
	v_pk_add_f32 v[164:165], v[166:167], v[164:165] op_sel_hi:[0,1]
	v_pk_fma_f32 v[164:165], v[150:151], v[150:151], v[164:165]
	v_mul_f32_e32 v166, v151, v151
	v_pk_add_f32 v[164:165], v[166:167], v[164:165] op_sel_hi:[0,1]
	v_pk_fma_f32 v[164:165], v[144:145], v[144:145], v[164:165]
	v_mul_f32_e32 v166, v145, v145
	v_pk_add_f32 v[164:165], v[166:167], v[164:165] op_sel_hi:[0,1]
	v_pk_fma_f32 v[164:165], v[148:149], v[148:149], v[164:165]
	v_mul_f32_e32 v166, v149, v149
	v_pk_add_f32 v[164:165], v[166:167], v[164:165] op_sel_hi:[0,1]
	v_pk_fma_f32 v[164:165], v[142:143], v[142:143], v[164:165]
	v_mul_f32_e32 v166, v143, v143
	v_pk_add_f32 v[164:165], v[166:167], v[164:165] op_sel_hi:[0,1]
	v_pk_fma_f32 v[164:165], v[152:153], v[152:153], v[164:165]
	v_mul_f32_e32 v166, v153, v153
	v_pk_add_f32 v[164:165], v[166:167], v[164:165] op_sel_hi:[0,1]
	v_mov_b32_e32 v17, v164
	s_nop 1
	v_permlane16_swap_b32_e32 v164, v17
	v_add_f32_e32 v17, v164, v17
	v_mov_b32_e32 v163, v17
	s_nop 1
	v_permlane32_swap_b32_e32 v17, v163
	v_add_f32_e32 v17, v17, v163
	v_fmamk_f32 v17, v17, 0x3c800000, v211
	ds_read_b128 v[164:167], v172
	ds_read_b128 v[178:181], v171
	v_rsq_f32_e32 v17, v17
	ds_read_b128 v[182:185], v15
	v_mov_b32_e32 v186, v17
	s_waitcnt lgkmcnt(2)
	v_pk_mul_f32 v[164:165], v[164:165], v[186:187] op_sel_hi:[1,0]
	s_waitcnt lgkmcnt(0)
	v_pk_mul_f32 v[182:183], v[182:183], v[186:187] op_sel_hi:[1,0]
	v_pk_mul_f32 v[146:147], v[146:147], v[164:165]
	v_pk_mul_f32 v[164:165], v[166:167], v[186:187] op_sel_hi:[1,0]
	v_pk_mul_f32 v[144:145], v[144:145], v[182:183]
	v_pk_mul_f32 v[150:151], v[150:151], v[164:165]
	ds_read_b128 v[164:167], v0
	v_pk_mul_f32 v[182:183], v[184:185], v[186:187] op_sel_hi:[1,0]
	s_waitcnt lgkmcnt(0)
	v_pk_mul_f32 v[164:165], v[164:165], v[186:187] op_sel_hi:[1,0]
	s_nop 0
	v_pk_mul_f32 v[142:143], v[142:143], v[164:165]
	v_pk_mul_f32 v[164:165], v[166:167], v[186:187] op_sel_hi:[1,0]
	v_pk_mul_f32 v[148:149], v[148:149], v[182:183]
	v_pk_mul_f32 v[152:153], v[152:153], v[164:165]
	v_pk_mul_f32 v[164:165], v[178:179], v[186:187] op_sel_hi:[1,0]
	s_nop 0
	v_pk_mul_f32 v[154:155], v[154:155], v[164:165]
	s_nop 0
	v_mov_b32_e32 v164, v155
	v_mov_b32_e32 v165, v155
	v_mov_b32_e32 v17, v154
	v_mov_b32_e32 v163, v154
	v_permlane32_swap_b32_e32 v164, v165
	s_nop 0
	v_permlane32_swap_b32_e32 v17, v163
	v_cndmask_b32_e64 v165, v164, v165, s[4:5]
	v_cndmask_b32_e64 v164, v17, v163, s[4:5]
	v_pk_mul_f32 v[164:165], v[10:11], v[164:165]
	s_nop 0
	v_cndmask_b32_e64 v165, v165, -v165, s[4:5]
	v_cndmask_b32_e64 v164, v164, -v164, s[4:5]
	v_pk_fma_f32 v[154:155], v[6:7], v[154:155], v[164:165]
	v_pk_mul_f32 v[164:165], v[180:181], v[186:187] op_sel_hi:[1,0]
	s_nop 0
	v_pk_mul_f32 v[156:157], v[156:157], v[164:165]
	s_nop 0
	v_mov_b32_e32 v164, v157
	v_mov_b32_e32 v165, v157
	v_mov_b32_e32 v17, v156
	v_mov_b32_e32 v163, v156
	v_permlane32_swap_b32_e32 v164, v165
	s_nop 0
	v_permlane32_swap_b32_e32 v17, v163
	v_cndmask_b32_e64 v165, v164, v165, s[4:5]
	v_cndmask_b32_e64 v164, v17, v163, s[4:5]
	v_pk_mul_f32 v[164:165], v[12:13], v[164:165]
	s_nop 0
	v_cndmask_b32_e64 v165, v165, -v165, s[4:5]
	v_cndmask_b32_e64 v164, v164, -v164, s[4:5]
	v_pk_fma_f32 v[156:157], v[8:9], v[156:157], v[164:165]
; DI float xsum16(float x) { const u32x2 r = __builtin_amdgcn_permlane16_swap(__float_as_uint(x), __float_as_uint(x), false, false); return __uint_as_float(r[0]) + __uint_as_float(r[1]); }
; DI float xsum32(float x) { const u32x2 r = __builtin_amdgcn_permlane32_swap(__float_as_uint(x), __float_as_uint(x), false, false); return __uint_as_float(r[0]) + __uint_as_float(r[1]); }
; template <int CT>
; DI void phase_g1(int c, int l) {
;     ...
;     for (int n = 0; n < 4; ++n) {
;       const int tt = wc * 64 + n * 16 + fr;
;       const float rs = rsqrtf(*(const float*)(shm + EXT_SSQ + tt * 4) * (1.f / 1024.f) + EPS) * (1.f / WQ_SCALE);
;       const f32x4 cs = *(const f32x4*)(shm + EXT_ROPE + tt * 64 + (fq & 1) * 16);
;       const f32x4 sn = *(const f32x4*)(shm + EXT_ROPE + tt * 64 + 32 + (fq & 1) * 16);
; #pragma unroll
;       for (int hs = 0; hs < 2; ++hs) {
;         const int f0 = fbase + wr * 128 + hs * 64;
;         const float* gain = gain_ptr(p, l, f0);
;         float v[4][4];
; #pragma unroll
;         for (int mm = 0; mm < 4; ++mm)
; #pragma unroll
;           for (int j = 0; j < 4; ++j) v[mm][j] = acc[hs * 4 + mm][n][j] * rs;
;         if (gain) {
;           float ss = 0.f;
; #pragma unroll
;           for (int mm = 0; mm < 4; ++mm)
; #pragma unroll
;             for (int j = 0; j < 4; ++j) ss += v[mm][j] * v[mm][j];
;           ss = xsum16(ss); ss = xsum32(ss);
;           const float inv = rsqrtf(ss * (1.f / 64.f) + EPS);
; #pragma unroll
;           for (int mm = 0; mm < 4; ++mm) {
;             const f32x4 gv = *(const f32x4*)(shm + EXT_GAIN + (wr * 128 + hs * 64 + mm * 16 + fq * 4) * 4);
; #pragma unroll
;             for (int j = 0; j < 4; ++j) v[mm][j] *= inv * gv[j];
;           }
; #pragma unroll
;           for (int j = 0; j < 4; ++j) {
;             const float pr = xother32(v[0][j]);
;             v[0][j] = (fq < 2) ? (v[0][j] * cs[j] - pr * sn[j]) : (v[0][j] * cs[j] + pr * sn[j]);
;           }
;         }
; #pragma unroll
;         for (int mm = 0; mm < 4; ++mm) {
;           uint2 o; o.x = pk2(v[mm][0], v[mm][1]); o.y = pk2(v[mm][2], v[mm][3]);
;           *(uint2*)(shm + tt * TP + (wr * 128 + hs * 64 + mm * 16 + fq * 4) * 2) = o;
;         }
.LBB0_513:
	v_add_u32_e32 v162, 0x2100, v162
	v_mov_b32_e32 v17, v16
	v_cvt_pk_bf16_f32 v154, v154, v155
	v_cvt_pk_bf16_f32 v155, v156, v157
	v_add_u32_e32 v156, v162, v175
	v_cvt_pk_bf16_f32 v146, v146, v147
	v_cvt_pk_bf16_f32 v147, v150, v151
	v_cvt_pk_bf16_f32 v144, v144, v145
	v_cvt_pk_bf16_f32 v145, v148, v149
	v_cvt_pk_bf16_f32 v142, v142, v143
	v_cvt_pk_bf16_f32 v143, v152, v153
	ds_write2_b64 v156, v[154:155], v[146:147] offset1:4
	ds_write2_b64 v156, v[144:145], v[142:143] offset0:8 offset1:12
	v_pk_mul_f32 v[152:153], v[2:3], v[16:17]
	v_pk_mul_f32 v[154:155], v[4:5], v[16:17]
	v_pk_mul_f32 v[146:147], v[58:59], v[16:17]
	v_pk_mul_f32 v[150:151], v[60:61], v[16:17]
	v_pk_mul_f32 v[144:145], v[22:23], v[16:17]
	v_pk_mul_f32 v[148:149], v[24:25], v[16:17]
	v_pk_mul_f32 v[142:143], v[18:19], v[16:17]
	s_and_b64 vcc, exec, s[8:9]
	v_pk_mul_f32 v[16:17], v[20:21], v[16:17]
	s_cbranch_vccnz .LBB0_515
	v_mul_f32_e32 v156, v153, v153
	v_pk_fma_f32 v[156:157], v[152:153], v[152:153], v[156:157] op_sel_hi:[1,1,0]
	v_mul_f32_e32 v164, v155, v155
	v_pk_fma_f32 v[156:157], v[154:155], v[154:155], v[156:157]
	s_nop 0
	v_pk_add_f32 v[156:157], v[164:165], v[156:157] op_sel_hi:[0,1]
	v_pk_fma_f32 v[156:157], v[146:147], v[146:147], v[156:157]
	v_mul_f32_e32 v164, v147, v147
	v_pk_add_f32 v[156:157], v[164:165], v[156:157] op_sel_hi:[0,1]
	v_pk_fma_f32 v[156:157], v[150:151], v[150:151], v[156:157]
	v_mul_f32_e32 v164, v151, v151
	v_pk_add_f32 v[156:157], v[164:165], v[156:157] op_sel_hi:[0,1]
	v_pk_fma_f32 v[156:157], v[144:145], v[144:145], v[156:157]
	v_mul_f32_e32 v164, v145, v145
	v_pk_add_f32 v[156:157], v[164:165], v[156:157] op_sel_hi:[0,1]
	v_pk_fma_f32 v[156:157], v[148:149], v[148:149], v[156:157]
	v_mul_f32_e32 v164, v149, v149
	v_pk_add_f32 v[156:157], v[164:165], v[156:157] op_sel_hi:[0,1]
	v_pk_fma_f32 v[156:157], v[142:143], v[142:143], v[156:157]
	v_mul_f32_e32 v164, v143, v143
	v_pk_add_f32 v[156:157], v[164:165], v[156:157] op_sel_hi:[0,1]
	v_pk_fma_f32 v[156:157], v[16:17], v[16:17], v[156:157]
	v_mul_f32_e32 v164, v17, v17
	v_pk_add_f32 v[156:157], v[164:165], v[156:157] op_sel_hi:[0,1]
	v_mov_b32_e32 v157, v156
	s_nop 1
	v_permlane16_swap_b32_e32 v156, v157
	v_add_f32_e32 v156, v156, v157
	v_mov_b32_e32 v157, v156
	s_nop 1
	v_permlane32_swap_b32_e32 v156, v157
	v_add_f32_e32 v156, v156, v157
	v_fmamk_f32 v156, v156, 0x3c800000, v211
	ds_read2_b32 v[164:165], v160 offset0:2 offset1:3
	ds_read2_b32 v[166:167], v161 offset0:2 offset1:3
	ds_read2_b32 v[178:179], v161 offset1:1
	ds_read2_b32 v[180:181], v160 offset1:1
	ds_read2_b32 v[182:183], v158 offset0:2 offset1:3
	ds_read2_b32 v[184:185], v159 offset0:2 offset1:3
	ds_read2_b32 v[186:187], v159 offset1:1
	ds_read2_b32 v[188:189], v158 offset1:1
	v_rsq_f32_e32 v156, v156
	s_nop 0
	s_waitcnt lgkmcnt(6)
	v_pk_mul_f32 v[166:167], v[166:167], v[156:157] op_sel_hi:[1,0]
	s_waitcnt lgkmcnt(5)
	v_pk_mul_f32 v[178:179], v[178:179], v[156:157] op_sel_hi:[1,0]
	v_pk_mul_f32 v[150:151], v[150:151], v[166:167]
	s_waitcnt lgkmcnt(0)
	v_pk_mul_f32 v[166:167], v[188:189], v[156:157] op_sel_hi:[1,0]
	v_pk_mul_f32 v[146:147], v[146:147], v[178:179]
	v_pk_mul_f32 v[144:145], v[144:145], v[166:167]
	v_pk_mul_f32 v[166:167], v[182:183], v[156:157] op_sel_hi:[1,0]
	s_nop 0
	v_pk_mul_f32 v[148:149], v[148:149], v[166:167]
	v_pk_mul_f32 v[166:167], v[186:187], v[156:157] op_sel_hi:[1,0]
	s_nop 0
	v_pk_mul_f32 v[142:143], v[142:143], v[166:167]
	v_pk_mul_f32 v[166:167], v[184:185], v[156:157] op_sel_hi:[1,0]
	s_nop 0
	v_pk_mul_f32 v[16:17], v[16:17], v[166:167]
	v_pk_mul_f32 v[166:167], v[180:181], v[156:157] op_sel_hi:[1,0]
	s_nop 0
	v_pk_mul_f32 v[152:153], v[152:153], v[166:167]
	s_nop 0
	v_mov_b32_e32 v166, v153
	v_mov_b32_e32 v167, v153
	v_mov_b32_e32 v157, v152
	v_mov_b32_e32 v163, v152
	v_permlane32_swap_b32_e32 v166, v167
	s_nop 0
	v_permlane32_swap_b32_e32 v157, v163
	v_cndmask_b32_e64 v167, v166, v167, s[4:5]
	v_cndmask_b32_e64 v166, v157, v163, s[4:5]
	v_pk_mul_f32 v[10:11], v[10:11], v[166:167]
	s_nop 0
	v_cndmask_b32_e64 v11, v11, -v11, s[4:5]
	v_cndmask_b32_e64 v10, v10, -v10, s[4:5]
	v_pk_fma_f32 v[152:153], v[6:7], v[152:153], v[10:11]
	v_pk_mul_f32 v[6:7], v[164:165], v[156:157] op_sel_hi:[1,0]
	s_nop 0
	v_pk_mul_f32 v[6:7], v[154:155], v[6:7]
	s_nop 0
	v_mov_b32_e32 v11, v7
	v_mov_b32_e32 v155, v7
	v_mov_b32_e32 v10, v6
	v_mov_b32_e32 v154, v6
	v_permlane32_swap_b32_e32 v11, v155
	s_nop 0
	v_permlane32_swap_b32_e32 v10, v154
	v_cndmask_b32_e64 v11, v11, v155, s[4:5]
	v_cndmask_b32_e64 v10, v10, v154, s[4:5]
	v_pk_mul_f32 v[10:11], v[12:13], v[10:11]
	s_nop 0
	v_cndmask_b32_e64 v11, v11, -v11, s[4:5]
	v_cndmask_b32_e64 v10, v10, -v10, s[4:5]
	v_pk_fma_f32 v[154:155], v[8:9], v[6:7], v[10:11]
; DI float xsum16(float x) { const u32x2 r = __builtin_amdgcn_permlane16_swap(__float_as_uint(x), __float_as_uint(x), false, false); return __uint_as_float(r[0]) + __uint_as_float(r[1]); }
; DI float xsum32(float x) { const u32x2 r = __builtin_amdgcn_permlane32_swap(__float_as_uint(x), __float_as_uint(x), false, false); return __uint_as_float(r[0]) + __uint_as_float(r[1]); }
; template <int CT>
; DI void phase_g1(int c, int l) {
;     ...
;     for (int n = 0; n < 4; ++n) {
;       const int tt = wc * 64 + n * 16 + fr;
;       const float rs = rsqrtf(*(const float*)(shm + EXT_SSQ + tt * 4) * (1.f / 1024.f) + EPS) * (1.f / WQ_SCALE);
;       const f32x4 cs = *(const f32x4*)(shm + EXT_ROPE + tt * 64 + (fq & 1) * 16);
;       const f32x4 sn = *(const f32x4*)(shm + EXT_ROPE + tt * 64 + 32 + (fq & 1) * 16);
; #pragma unroll
;       for (int hs = 0; hs < 2; ++hs) {
;         const int f0 = fbase + wr * 128 + hs * 64;
;         const float* gain = gain_ptr(p, l, f0);
;         float v[4][4];
; #pragma unroll
;         for (int mm = 0; mm < 4; ++mm)
; #pragma unroll
;           for (int j = 0; j < 4; ++j) v[mm][j] = acc[hs * 4 + mm][n][j] * rs;
;         if (gain) {
;           float ss = 0.f;
; #pragma unroll
;           for (int mm = 0; mm < 4; ++mm)
; #pragma unroll
;             for (int j = 0; j < 4; ++j) ss += v[mm][j] * v[mm][j];
;           ss = xsum16(ss); ss = xsum32(ss);
;           const float inv = rsqrtf(ss * (1.f / 64.f) + EPS);
; #pragma unroll
;           for (int mm = 0; mm < 4; ++mm) {
;             const f32x4 gv = *(const f32x4*)(shm + EXT_GAIN + (wr * 128 + hs * 64 + mm * 16 + fq * 4) * 4);
; #pragma unroll
;             for (int j = 0; j < 4; ++j) v[mm][j] *= inv * gv[j];
;           }
; #pragma unroll
;           for (int j = 0; j < 4; ++j) {
;             const float pr = xother32(v[0][j]);
;             v[0][j] = (fq < 2) ? (v[0][j] * cs[j] - pr * sn[j]) : (v[0][j] * cs[j] + pr * sn[j]);
;           }
;         }
; #pragma unroll
;         for (int mm = 0; mm < 4; ++mm) {
;           uint2 o; o.x = pk2(v[mm][0], v[mm][1]); o.y = pk2(v[mm][2], v[mm][3]);
;           *(uint2*)(shm + tt * TP + (wr * 128 + hs * 64 + mm * 16 + fq * 4) * 2) = o;
;         }
.LBB0_515:
	s_waitcnt lgkmcnt(3)
	v_cvt_pk_bf16_f32 v6, v152, v153
	v_cvt_pk_bf16_f32 v7, v154, v155
	s_waitcnt lgkmcnt(2)
	v_add_u32_e32 v10, v162, v176
	v_cvt_pk_bf16_f32 v8, v146, v147
	v_cvt_pk_bf16_f32 v9, v150, v151
	ds_write2_b64 v10, v[6:7], v[8:9] offset1:4
	v_cvt_pk_bf16_f32 v6, v144, v145
	v_cvt_pk_bf16_f32 v7, v148, v149
	v_cvt_pk_bf16_f32 v8, v142, v143
	v_cvt_pk_bf16_f32 v9, v16, v17
	ds_write2_b64 v10, v[6:7], v[8:9] offset0:8 offset1:12
	v_or_b32_e32 v6, 48, v174
	v_lshl_or_b32 v7, v6, 2, v253
	ds_read_b32 v10, v7
	v_lshl_or_b32 v6, v6, 6, v173
	v_add_u32_e32 v11, 0x21000, v6
	ds_read_b128 v[6:9], v11
	s_waitcnt lgkmcnt(1)
	v_fmamk_f32 v10, v10, 0x3a800000, v211
	v_rsq_f32_e32 v10, v10
	s_nop 0
	v_mul_f32_e32 v16, 0x3d000000, v10
	ds_read_b128 v[10:13], v11 offset:32
	v_pk_mul_f32 v[154:155], v[54:55], v[16:17] op_sel_hi:[1,0]
	v_pk_mul_f32 v[156:157], v[56:57], v[16:17] op_sel_hi:[1,0]
	v_pk_mul_f32 v[146:147], v[50:51], v[16:17] op_sel_hi:[1,0]
	v_pk_mul_f32 v[150:151], v[52:53], v[16:17] op_sel_hi:[1,0]
	v_pk_mul_f32 v[144:145], v[46:47], v[16:17] op_sel_hi:[1,0]
	v_pk_mul_f32 v[148:149], v[48:49], v[16:17] op_sel_hi:[1,0]
	v_pk_mul_f32 v[142:143], v[42:43], v[16:17] op_sel_hi:[1,0]
	s_and_b64 vcc, exec, s[6:7]
	v_pk_mul_f32 v[152:153], v[44:45], v[16:17] op_sel_hi:[1,0]
	s_cbranch_vccnz .LBB0_517
	v_mul_f32_e32 v164, v155, v155
	v_pk_fma_f32 v[164:165], v[154:155], v[154:155], v[164:165] op_sel_hi:[1,1,0]
	v_mul_f32_e32 v166, v157, v157
	v_pk_fma_f32 v[164:165], v[156:157], v[156:157], v[164:165]
	s_nop 0
	v_pk_add_f32 v[164:165], v[166:167], v[164:165] op_sel_hi:[0,1]
	v_pk_fma_f32 v[164:165], v[146:147], v[146:147], v[164:165]
	v_mul_f32_e32 v166, v147, v147
	v_pk_add_f32 v[164:165], v[166:167], v[164:165] op_sel_hi:[0,1]
	v_pk_fma_f32 v[164:165], v[150:151], v[150:151], v[164:165]
	v_mul_f32_e32 v166, v151, v151
	v_pk_add_f32 v[164:165], v[166:167], v[164:165] op_sel_hi:[0,1]
	v_pk_fma_f32 v[164:165], v[144:145], v[144:145], v[164:165]
	v_mul_f32_e32 v166, v145, v145
	v_pk_add_f32 v[164:165], v[166:167], v[164:165] op_sel_hi:[0,1]
	v_pk_fma_f32 v[164:165], v[148:149], v[148:149], v[164:165]
	v_mul_f32_e32 v166, v149, v149
	v_pk_add_f32 v[164:165], v[166:167], v[164:165] op_sel_hi:[0,1]
	v_pk_fma_f32 v[164:165], v[142:143], v[142:143], v[164:165]
	v_mul_f32_e32 v166, v143, v143
	v_pk_add_f32 v[164:165], v[166:167], v[164:165] op_sel_hi:[0,1]
	v_pk_fma_f32 v[164:165], v[152:153], v[152:153], v[164:165]
	v_mul_f32_e32 v166, v153, v153
	v_pk_add_f32 v[164:165], v[166:167], v[164:165] op_sel_hi:[0,1]
	v_mov_b32_e32 v17, v164
	s_nop 1
	v_permlane16_swap_b32_e32 v164, v17
	v_add_f32_e32 v17, v164, v17
	v_mov_b32_e32 v163, v17
	s_nop 1
	v_permlane32_swap_b32_e32 v17, v163
	v_add_f32_e32 v17, v17, v163
	v_fmamk_f32 v17, v17, 0x3c800000, v211
	ds_read_b128 v[164:167], v172
	ds_read_b128 v[178:181], v171
	v_rsq_f32_e32 v17, v17
	ds_read_b128 v[182:185], v15
	v_mov_b32_e32 v172, v17
	s_waitcnt lgkmcnt(2)
	v_pk_mul_f32 v[164:165], v[164:165], v[172:173] op_sel_hi:[1,0]
	s_waitcnt lgkmcnt(0)
	v_pk_mul_f32 v[182:183], v[182:183], v[172:173] op_sel_hi:[1,0]
	v_pk_mul_f32 v[146:147], v[146:147], v[164:165]
	v_pk_mul_f32 v[164:165], v[166:167], v[172:173] op_sel_hi:[1,0]
	v_pk_mul_f32 v[144:145], v[144:145], v[182:183]
	v_pk_mul_f32 v[150:151], v[150:151], v[164:165]
	ds_read_b128 v[164:167], v0
	v_pk_mul_f32 v[182:183], v[184:185], v[172:173] op_sel_hi:[1,0]
	s_waitcnt lgkmcnt(0)
	v_pk_mul_f32 v[164:165], v[164:165], v[172:173] op_sel_hi:[1,0]
	s_nop 0
	v_pk_mul_f32 v[142:143], v[142:143], v[164:165]
	v_pk_mul_f32 v[164:165], v[166:167], v[172:173] op_sel_hi:[1,0]
	v_pk_mul_f32 v[148:149], v[148:149], v[182:183]
	v_pk_mul_f32 v[152:153], v[152:153], v[164:165]
	v_pk_mul_f32 v[164:165], v[178:179], v[172:173] op_sel_hi:[1,0]
	s_nop 0
	v_pk_mul_f32 v[154:155], v[154:155], v[164:165]
	s_nop 0
	v_mov_b32_e32 v17, v155
	v_mov_b32_e32 v163, v155
	v_mov_b32_e32 v0, v154
	v_mov_b32_e32 v15, v154
	v_permlane32_swap_b32_e32 v17, v163
	s_nop 0
	v_permlane32_swap_b32_e32 v0, v15
	v_cndmask_b32_e64 v165, v17, v163, s[4:5]
	v_cndmask_b32_e64 v164, v0, v15, s[4:5]
	v_pk_mul_f32 v[164:165], v[10:11], v[164:165]
	s_nop 0
	v_cndmask_b32_e64 v165, v165, -v165, s[4:5]
	v_cndmask_b32_e64 v164, v164, -v164, s[4:5]
	v_pk_fma_f32 v[154:155], v[6:7], v[154:155], v[164:165]
	v_pk_mul_f32 v[164:165], v[180:181], v[172:173] op_sel_hi:[1,0]
	s_nop 0
	v_pk_mul_f32 v[156:157], v[156:157], v[164:165]
	s_nop 0
	v_mov_b32_e32 v17, v157
	v_mov_b32_e32 v163, v157
	v_mov_b32_e32 v0, v156
	v_mov_b32_e32 v15, v156
	v_permlane32_swap_b32_e32 v17, v163
	s_nop 0
	v_permlane32_swap_b32_e32 v0, v15
	v_cndmask_b32_e64 v165, v17, v163, s[4:5]
	v_cndmask_b32_e64 v164, v0, v15, s[4:5]
	v_pk_mul_f32 v[164:165], v[12:13], v[164:165]
	s_nop 0
	v_cndmask_b32_e64 v165, v165, -v165, s[4:5]
	v_cndmask_b32_e64 v164, v164, -v164, s[4:5]
	v_pk_fma_f32 v[156:157], v[8:9], v[156:157], v[164:165]
; DI float xsum16(float x) { const u32x2 r = __builtin_amdgcn_permlane16_swap(__float_as_uint(x), __float_as_uint(x), false, false); return __uint_as_float(r[0]) + __uint_as_float(r[1]); }
; DI float xsum32(float x) { const u32x2 r = __builtin_amdgcn_permlane32_swap(__float_as_uint(x), __float_as_uint(x), false, false); return __uint_as_float(r[0]) + __uint_as_float(r[1]); }
; template <int CT>
; DI void phase_g1(int c, int l) {
;     ...
;     for (int n = 0; n < 4; ++n) {
;       const int tt = wc * 64 + n * 16 + fr;
;       const float rs = rsqrtf(*(const float*)(shm + EXT_SSQ + tt * 4) * (1.f / 1024.f) + EPS) * (1.f / WQ_SCALE);
;       const f32x4 cs = *(const f32x4*)(shm + EXT_ROPE + tt * 64 + (fq & 1) * 16);
;       const f32x4 sn = *(const f32x4*)(shm + EXT_ROPE + tt * 64 + 32 + (fq & 1) * 16);
; #pragma unroll
;       for (int hs = 0; hs < 2; ++hs) {
;         const int f0 = fbase + wr * 128 + hs * 64;
;         const float* gain = gain_ptr(p, l, f0);
;         float v[4][4];
; #pragma unroll
;         for (int mm = 0; mm < 4; ++mm)
; #pragma unroll
;           for (int j = 0; j < 4; ++j) v[mm][j] = acc[hs * 4 + mm][n][j] * rs;
;         if (gain) {
;           float ss = 0.f;
; #pragma unroll
;           for (int mm = 0; mm < 4; ++mm)
; #pragma unroll
;             for (int j = 0; j < 4; ++j) ss += v[mm][j] * v[mm][j];
;           ss = xsum16(ss); ss = xsum32(ss);
;           const float inv = rsqrtf(ss * (1.f / 64.f) + EPS);
; #pragma unroll
;           for (int mm = 0; mm < 4; ++mm) {
;             const f32x4 gv = *(const f32x4*)(shm + EXT_GAIN + (wr * 128 + hs * 64 + mm * 16 + fq * 4) * 4);
; #pragma unroll
;             for (int j = 0; j < 4; ++j) v[mm][j] *= inv * gv[j];
;           }
; #pragma unroll
;           for (int j = 0; j < 4; ++j) {
;             const float pr = xother32(v[0][j]);
;             v[0][j] = (fq < 2) ? (v[0][j] * cs[j] - pr * sn[j]) : (v[0][j] * cs[j] + pr * sn[j]);
;           }
;         }
; #pragma unroll
;         for (int mm = 0; mm < 4; ++mm) {
;           uint2 o; o.x = pk2(v[mm][0], v[mm][1]); o.y = pk2(v[mm][2], v[mm][3]);
;           *(uint2*)(shm + tt * TP + (wr * 128 + hs * 64 + mm * 16 + fq * 4) * 2) = o;
;         }
.LBB0_517:
	v_add_u32_e32 v0, 0x2100, v162
	v_mov_b32_e32 v17, v16
	v_cvt_pk_bf16_f32 v154, v154, v155
	v_cvt_pk_bf16_f32 v155, v156, v157
	v_add_u32_e32 v15, v0, v175
	v_cvt_pk_bf16_f32 v146, v146, v147
	v_cvt_pk_bf16_f32 v147, v150, v151
	v_cvt_pk_bf16_f32 v144, v144, v145
	v_cvt_pk_bf16_f32 v145, v148, v149
	v_cvt_pk_bf16_f32 v142, v142, v143
	v_cvt_pk_bf16_f32 v143, v152, v153
	ds_write2_b64 v15, v[154:155], v[146:147] offset1:4
	ds_write2_b64 v15, v[144:145], v[142:143] offset0:8 offset1:12
	v_pk_mul_f32 v[152:153], v[38:39], v[16:17]
	v_pk_mul_f32 v[154:155], v[40:41], v[16:17]
	v_pk_mul_f32 v[146:147], v[34:35], v[16:17]
	v_pk_mul_f32 v[150:151], v[36:37], v[16:17]
	v_pk_mul_f32 v[144:145], v[30:31], v[16:17]
	v_pk_mul_f32 v[148:149], v[32:33], v[16:17]
	v_pk_mul_f32 v[142:143], v[26:27], v[16:17]
	s_and_b64 vcc, exec, s[8:9]
	v_pk_mul_f32 v[16:17], v[28:29], v[16:17]
	s_cbranch_vccnz .LBB0_519
	v_mul_f32_e32 v156, v153, v153
	v_pk_fma_f32 v[156:157], v[152:153], v[152:153], v[156:157] op_sel_hi:[1,1,0]
	v_mul_f32_e32 v162, v155, v155
	v_pk_fma_f32 v[156:157], v[154:155], v[154:155], v[156:157]
	s_nop 0
	v_pk_add_f32 v[156:157], v[162:163], v[156:157] op_sel_hi:[0,1]
	v_pk_fma_f32 v[156:157], v[146:147], v[146:147], v[156:157]
	v_mul_f32_e32 v162, v147, v147
	v_pk_add_f32 v[156:157], v[162:163], v[156:157] op_sel_hi:[0,1]
	v_pk_fma_f32 v[156:157], v[150:151], v[150:151], v[156:157]
	v_mul_f32_e32 v162, v151, v151
	v_pk_add_f32 v[156:157], v[162:163], v[156:157] op_sel_hi:[0,1]
	v_pk_fma_f32 v[156:157], v[144:145], v[144:145], v[156:157]
	v_mul_f32_e32 v162, v145, v145
	v_pk_add_f32 v[156:157], v[162:163], v[156:157] op_sel_hi:[0,1]
	v_pk_fma_f32 v[156:157], v[148:149], v[148:149], v[156:157]
	v_mul_f32_e32 v162, v149, v149
	v_pk_add_f32 v[156:157], v[162:163], v[156:157] op_sel_hi:[0,1]
	v_pk_fma_f32 v[156:157], v[142:143], v[142:143], v[156:157]
	v_mul_f32_e32 v162, v143, v143
	v_pk_add_f32 v[156:157], v[162:163], v[156:157] op_sel_hi:[0,1]
	v_pk_fma_f32 v[156:157], v[16:17], v[16:17], v[156:157]
	v_mul_f32_e32 v162, v17, v17
	v_pk_add_f32 v[156:157], v[162:163], v[156:157] op_sel_hi:[0,1]
	v_mov_b32_e32 v15, v156
	s_nop 1
	v_permlane16_swap_b32_e32 v156, v15
	v_add_f32_e32 v15, v156, v15
	v_mov_b32_e32 v156, v15
	s_nop 1
	v_permlane32_swap_b32_e32 v15, v156
	v_add_f32_e32 v15, v15, v156
	v_fmamk_f32 v15, v15, 0x3c800000, v211
	ds_read2_b32 v[162:163], v160 offset0:2 offset1:3
	ds_read2_b32 v[164:165], v161 offset0:2 offset1:3
	ds_read2_b32 v[166:167], v161 offset1:1
	ds_read2_b32 v[160:161], v160 offset1:1
	ds_read2_b32 v[172:173], v158 offset0:2 offset1:3
	ds_read2_b32 v[174:175], v159 offset0:2 offset1:3
	ds_read2_b32 v[178:179], v159 offset1:1
	ds_read2_b32 v[158:159], v158 offset1:1
	v_rsq_f32_e32 v15, v15
	s_nop 0
	v_mov_b32_e32 v156, v15
	s_waitcnt lgkmcnt(0)
	v_pk_mul_f32 v[158:159], v[158:159], v[156:157] op_sel_hi:[1,0]
	v_pk_mul_f32 v[166:167], v[166:167], v[156:157] op_sel_hi:[1,0]
	v_pk_mul_f32 v[144:145], v[144:145], v[158:159]
	v_pk_mul_f32 v[158:159], v[172:173], v[156:157] op_sel_hi:[1,0]
	v_pk_mul_f32 v[164:165], v[164:165], v[156:157] op_sel_hi:[1,0]
	v_pk_mul_f32 v[148:149], v[148:149], v[158:159]
	v_pk_mul_f32 v[158:159], v[178:179], v[156:157] op_sel_hi:[1,0]
	v_pk_mul_f32 v[146:147], v[146:147], v[166:167]
	v_pk_mul_f32 v[142:143], v[142:143], v[158:159]
	v_pk_mul_f32 v[158:159], v[174:175], v[156:157] op_sel_hi:[1,0]
	v_pk_mul_f32 v[150:151], v[150:151], v[164:165]
	v_pk_mul_f32 v[16:17], v[16:17], v[158:159]
	v_pk_mul_f32 v[158:159], v[160:161], v[156:157] op_sel_hi:[1,0]
	s_nop 0
	v_pk_mul_f32 v[152:153], v[152:153], v[158:159]
	s_nop 0
	v_mov_b32_e32 v158, v153
	v_mov_b32_e32 v159, v153
	v_mov_b32_e32 v15, v152
	v_mov_b32_e32 v157, v152
	v_permlane32_swap_b32_e32 v158, v159
	s_nop 0
	v_permlane32_swap_b32_e32 v15, v157
	v_cndmask_b32_e64 v159, v158, v159, s[4:5]
	v_cndmask_b32_e64 v158, v15, v157, s[4:5]
	v_pk_mul_f32 v[10:11], v[10:11], v[158:159]
	s_nop 0
	v_cndmask_b32_e64 v11, v11, -v11, s[4:5]
	v_cndmask_b32_e64 v10, v10, -v10, s[4:5]
	v_pk_fma_f32 v[152:153], v[6:7], v[152:153], v[10:11]
	v_pk_mul_f32 v[6:7], v[162:163], v[156:157] op_sel_hi:[1,0]
	s_nop 0
	v_pk_mul_f32 v[6:7], v[154:155], v[6:7]
	s_nop 0
	v_mov_b32_e32 v11, v7
	v_mov_b32_e32 v154, v7
	v_mov_b32_e32 v10, v6
	v_mov_b32_e32 v15, v6
	v_permlane32_swap_b32_e32 v11, v154
	s_nop 0
	v_permlane32_swap_b32_e32 v10, v15
	v_cndmask_b32_e64 v11, v11, v154, s[4:5]
	v_cndmask_b32_e64 v10, v10, v15, s[4:5]
	v_pk_mul_f32 v[10:11], v[12:13], v[10:11]
	s_nop 0
	v_cndmask_b32_e64 v11, v11, -v11, s[4:5]
	v_cndmask_b32_e64 v10, v10, -v10, s[4:5]
	v_pk_fma_f32 v[154:155], v[8:9], v[6:7], v[10:11]

; #define LOAD_PARAMS() KParams kq_ = (KParams)__builtin_amdgcn_kernarg_segment_ptr(); asm volatile("" : "+s"(kq_)); const Params p = *kq_
; template <int CT>
; __global__ void __launch_bounds__(NTHREADS) mega_kernel(Params p) {
;     ...
; #pragma unroll 1
;   for (int ph = 0; ph < nph; ++ph) {
;     run_phase<CT>(ph);
;     if (ph + 1 < nph) {
;       LOAD_PARAMS();
;       xcd_barrier((unsigned*)(p.ws + WS<CT>::bar), x, nloc, nx, k);
;       ++k;
;     }
;   }
; }
.LBB0_726:
	s_endpgm
	s_nop 0
	s_nop 0
	s_nop 0
	s_nop 0
	s_nop 0
	s_nop 0
	s_nop 0
	s_nop 0
	s_nop 0
	s_nop 0
	s_nop 0
	s_nop 0
	s_nop 0
	s_nop 0
	s_nop 0
	s_nop 0
	s_nop 0
	s_nop 0
	s_nop 0
	s_nop 0
	s_nop 0
	s_nop 0
	s_nop 0
	s_nop 0
	s_nop 0
	s_nop 0
	s_nop 0
	s_nop 0
	s_nop 0
	s_nop 0
	s_nop 0
	s_nop 0
	s_nop 0
	s_nop 0
	s_nop 0
	s_nop 0
	s_nop 0
	s_nop 0
	s_nop 0
	s_nop 0
	s_nop 0
	s_nop 0
	s_nop 0
	s_endpgm
